# GU: row-scale loads issued inside the last K-iteration (ahead of the prefetch DMAs); epilogue no longer waits on vmcnt
# speedup vs baseline: 1.0353x; 1.0085x over previous
.LBB0_1103:
	s_add_u32 s0, s2, 0xfffc0080
	s_addc_u32 s24, s3, -1
	s_add_i32 s30, 0, 0x10000
	s_cmp_eq_u32 s83, 12
	s_cselect_b32 s43, s17, s24
	s_cselect_b32 s42, s54, s0
	v_add_u32_e32 v0, s30, v178
	s_cselect_b32 s25, s15, s82
	s_cselect_b32 s24, s55, s71
	s_add_i32 s0, 0, 0x14000
	ds_read_b128 v[130:133], v0
	ds_read_b128 v[146:149], v0 offset:1024
	ds_read_b128 v[150:153], v0 offset:2048
	ds_read_b128 v[154:157], v0 offset:3072
	v_add_u32_e32 v0, s0, v178
	ds_read_b128 v[158:161], v0
	ds_read_b128 v[162:165], v0 offset:1024
	ds_read_b128 v[166:169], v0 offset:2048
	ds_read_b128 v[170:173], v0 offset:3072
	s_cmp_eq_u32 s83, 12
	s_cbranch_scc0 .Lgu_pa_skip
	s_lshl_b32 s100, s29, 8
	s_add_i32 s100, s100, s77
	v_and_or_b32 v252, v193, 15, s100
	v_bfe_u32 v253, v193, 4, 2
	v_lshlrev_b32_e32 v252, 6, v252
	v_lshl_add_u32 v252, v253, 4, v252
	global_load_dwordx4 v[194:197], v252, s[10:11]
	global_load_dwordx4 v[198:201], v252, s[10:11] offset:1024
	global_load_dwordx4 v[202:205], v252, s[10:11] offset:2048
	global_load_dwordx4 v[206:209], v252, s[10:11] offset:3072
.Lgu_pa_skip:
	v_lshl_add_u64 v[218:219], s[2:3], 0, v[144:145]
	s_add_i32 m0, s73, 0xc000
	ds_read_b128 v[174:177], v179
	ds_read_b128 v[180:183], v179 offset:1024
	ds_read_b128 v[184:187], v179 offset:2048
	ds_read_b128 v[188:191], v179 offset:3072
	ds_read_b128 v[214:217], v179 offset:4096
	ds_read_b128 v[228:231], v179 offset:5120
	ds_read_b128 v[232:235], v179 offset:6144
	ds_read_b128 v[236:239], v179 offset:7168
	global_load_lds_dwordx4 v[218:219], off
	v_lshl_add_u64 v[218:219], s[2:3], 0, v[142:143]
	s_add_i32 m0, s73, 0xe000
	s_nop 0
	global_load_lds_dwordx4 v[218:219], off
	s_waitcnt vmcnt(8)
	s_waitcnt lgkmcnt(0)
	s_barrier
	s_setprio 1
	s_waitcnt lgkmcnt(0)
	v_mfma_f32_16x16x32_bf16 v[122:125], v[130:133], v[174:177], v[122:125]
	v_mfma_f32_16x16x32_bf16 v[114:117], v[150:153], v[174:177], v[114:117]
	v_mfma_f32_16x16x32_bf16 v[106:109], v[130:133], v[184:187], v[106:109]
	v_mfma_f32_16x16x32_bf16 v[98:101], v[150:153], v[184:187], v[98:101]
	v_mfma_f32_16x16x32_bf16 v[90:93], v[130:133], v[214:217], v[90:93]
	v_mfma_f32_16x16x32_bf16 v[82:85], v[150:153], v[214:217], v[82:85]
	v_mfma_f32_16x16x32_bf16 v[74:77], v[130:133], v[232:235], v[74:77]
	v_mfma_f32_16x16x32_bf16 v[66:69], v[150:153], v[232:235], v[66:69]
	v_mfma_f32_16x16x32_bf16 v[122:125], v[146:149], v[180:183], v[122:125]
	v_mfma_f32_16x16x32_bf16 v[114:117], v[154:157], v[180:183], v[114:117]
	v_mfma_f32_16x16x32_bf16 v[106:109], v[146:149], v[188:191], v[106:109]
	v_mfma_f32_16x16x32_bf16 v[98:101], v[154:157], v[188:191], v[98:101]
	v_mfma_f32_16x16x32_bf16 v[90:93], v[146:149], v[228:231], v[90:93]
	v_mfma_f32_16x16x32_bf16 v[82:85], v[154:157], v[228:231], v[82:85]
	v_mfma_f32_16x16x32_bf16 v[74:77], v[146:149], v[236:239], v[74:77]
	v_mfma_f32_16x16x32_bf16 v[66:69], v[154:157], v[236:239], v[66:69]
	s_setprio 0
	s_setprio 1
	v_mfma_f32_16x16x32_bf16 v[126:129], v[158:161], v[174:177], v[126:129]
	v_mfma_f32_16x16x32_bf16 v[118:121], v[166:169], v[174:177], v[118:121]
	v_mfma_f32_16x16x32_bf16 v[110:113], v[158:161], v[184:187], v[110:113]
	v_mfma_f32_16x16x32_bf16 v[102:105], v[166:169], v[184:187], v[102:105]
	v_mfma_f32_16x16x32_bf16 v[94:97], v[158:161], v[214:217], v[94:97]
	v_mfma_f32_16x16x32_bf16 v[86:89], v[166:169], v[214:217], v[86:89]
	v_mfma_f32_16x16x32_bf16 v[78:81], v[158:161], v[232:235], v[78:81]
	v_mfma_f32_16x16x32_bf16 v[70:73], v[166:169], v[232:235], v[70:73]
	v_mfma_f32_16x16x32_bf16 v[126:129], v[162:165], v[180:183], v[126:129]
	v_mfma_f32_16x16x32_bf16 v[118:121], v[170:173], v[180:183], v[118:121]
	v_mfma_f32_16x16x32_bf16 v[110:113], v[162:165], v[188:191], v[110:113]
	v_mfma_f32_16x16x32_bf16 v[102:105], v[170:173], v[188:191], v[102:105]
	v_mfma_f32_16x16x32_bf16 v[94:97], v[162:165], v[228:231], v[94:97]
	v_mfma_f32_16x16x32_bf16 v[86:89], v[170:173], v[228:231], v[86:89]
	v_mfma_f32_16x16x32_bf16 v[78:81], v[162:165], v[236:239], v[78:81]
	v_mfma_f32_16x16x32_bf16 v[70:73], v[170:173], v[236:239], v[70:73]
	s_setprio 0
	s_barrier
	s_add_i32 s30, s30, s72
	v_lshl_add_u64 v[218:219], s[24:25], 0, v[138:139]
	s_mov_b32 m0, s30
	ds_read_b128 v[174:177], v179 offset:16384
	ds_read_b128 v[180:183], v179 offset:17408
	ds_read_b128 v[184:187], v179 offset:18432
	ds_read_b128 v[188:191], v179 offset:19456
	ds_read_b128 v[214:217], v179 offset:20480
	ds_read_b128 v[228:231], v179 offset:21504
	ds_read_b128 v[232:235], v179 offset:22528
	ds_read_b128 v[236:239], v179 offset:23552
	global_load_lds_dwordx4 v[218:219], off
	s_add_i32 m0, s30, 0x2000
	s_add_u32 s64, s24, 0x40000
	v_lshl_add_u64 v[240:241], s[24:25], 0, v[134:135]
	s_addc_u32 s65, s25, 0
	s_add_i32 s0, s0, s72
	global_load_lds_dwordx4 v[240:241], off
	v_lshl_add_u64 v[242:243], s[64:65], 0, v[138:139]
	s_mov_b32 m0, s0
	v_lshl_add_u64 v[244:245], s[42:43], 0, v[136:137]
	global_load_lds_dwordx4 v[242:243], off
	v_lshl_add_u64 v[242:243], s[64:65], 0, v[134:135]
	s_add_i32 m0, s0, 0x2000
	s_nop 0
	global_load_lds_dwordx4 v[242:243], off
	v_lshl_add_u64 v[242:243], s[42:43], 0, v[140:141]
	s_mov_b32 m0, s73
	s_nop 0
	global_load_lds_dwordx4 v[242:243], off
	s_mov_b32 m0, s74
	s_nop 0
	global_load_lds_dwordx4 v[244:245], off
	s_waitcnt vmcnt(8)
	s_waitcnt lgkmcnt(0)
	s_barrier
	s_setprio 1
	s_waitcnt lgkmcnt(0)
	v_mfma_f32_16x16x32_bf16 v[58:61], v[130:133], v[174:177], v[58:61]
	v_mfma_f32_16x16x32_bf16 v[50:53], v[150:153], v[174:177], v[50:53]
	v_mfma_f32_16x16x32_bf16 v[42:45], v[130:133], v[184:187], v[42:45]
	v_mfma_f32_16x16x32_bf16 v[34:37], v[150:153], v[184:187], v[34:37]
	v_mfma_f32_16x16x32_bf16 v[26:29], v[130:133], v[214:217], v[26:29]
	v_mfma_f32_16x16x32_bf16 v[18:21], v[150:153], v[214:217], v[18:21]
	v_mfma_f32_16x16x32_bf16 v[10:13], v[130:133], v[232:235], v[10:13]
	v_mfma_f32_16x16x32_bf16 v[6:9], v[150:153], v[232:235], v[6:9]
	v_mfma_f32_16x16x32_bf16 v[58:61], v[146:149], v[180:183], v[58:61]
	v_mfma_f32_16x16x32_bf16 v[50:53], v[154:157], v[180:183], v[50:53]
	v_mfma_f32_16x16x32_bf16 v[42:45], v[146:149], v[188:191], v[42:45]
	v_mfma_f32_16x16x32_bf16 v[34:37], v[154:157], v[188:191], v[34:37]
	v_mfma_f32_16x16x32_bf16 v[26:29], v[146:149], v[228:231], v[26:29]
	v_mfma_f32_16x16x32_bf16 v[18:21], v[154:157], v[228:231], v[18:21]
	v_mfma_f32_16x16x32_bf16 v[10:13], v[146:149], v[236:239], v[10:13]
	v_mfma_f32_16x16x32_bf16 v[6:9], v[154:157], v[236:239], v[6:9]
	s_setprio 0
	s_setprio 1
	v_mfma_f32_16x16x32_bf16 v[62:65], v[158:161], v[174:177], v[62:65]
	v_mfma_f32_16x16x32_bf16 v[54:57], v[166:169], v[174:177], v[54:57]
	v_mfma_f32_16x16x32_bf16 v[46:49], v[158:161], v[184:187], v[46:49]
	v_mfma_f32_16x16x32_bf16 v[38:41], v[166:169], v[184:187], v[38:41]
	v_mfma_f32_16x16x32_bf16 v[30:33], v[158:161], v[214:217], v[30:33]
	v_mfma_f32_16x16x32_bf16 v[22:25], v[166:169], v[214:217], v[22:25]
	v_mfma_f32_16x16x32_bf16 v[14:17], v[158:161], v[232:235], v[14:17]
	v_mfma_f32_16x16x32_bf16 v[2:5], v[166:169], v[232:235], v[2:5]
	v_mfma_f32_16x16x32_bf16 v[62:65], v[162:165], v[180:183], v[62:65]
	v_mfma_f32_16x16x32_bf16 v[54:57], v[170:173], v[180:183], v[54:57]
	v_mfma_f32_16x16x32_bf16 v[46:49], v[162:165], v[188:191], v[46:49]
	v_mfma_f32_16x16x32_bf16 v[38:41], v[170:173], v[188:191], v[38:41]
	v_mfma_f32_16x16x32_bf16 v[30:33], v[162:165], v[228:231], v[30:33]
	v_mfma_f32_16x16x32_bf16 v[22:25], v[170:173], v[228:231], v[22:25]
	v_mfma_f32_16x16x32_bf16 v[14:17], v[162:165], v[236:239], v[14:17]
	v_mfma_f32_16x16x32_bf16 v[2:5], v[170:173], v[236:239], v[2:5]
	s_setprio 0
	s_barrier
	s_add_i32 s0, 0, 0x18000
	v_add_u32_e32 v0, s0, v178
	s_add_i32 s30, 0, 0x1c000
	ds_read_b128 v[130:133], v0
	ds_read_b128 v[146:149], v0 offset:1024
	ds_read_b128 v[150:153], v0 offset:2048
	ds_read_b128 v[154:157], v0 offset:3072
	v_add_u32_e32 v0, s30, v178
	ds_read_b128 v[158:161], v0
	ds_read_b128 v[162:165], v0 offset:1024
	ds_read_b128 v[166:169], v0 offset:2048
	ds_read_b128 v[170:173], v0 offset:3072
	s_add_u32 s42, s42, 0x40000
	s_addc_u32 s43, s43, 0
	s_mov_b32 m0, s75
	v_lshl_add_u64 v[246:247], s[42:43], 0, v[140:141]
	ds_read_b128 v[174:177], v179 offset:32768
	ds_read_b128 v[180:183], v179 offset:33792
	ds_read_b128 v[184:187], v179 offset:34816
	ds_read_b128 v[188:191], v179 offset:35840
	ds_read_b128 v[214:217], v179 offset:36864
	ds_read_b128 v[228:231], v179 offset:37888
	ds_read_b128 v[232:235], v179 offset:38912
	ds_read_b128 v[236:239], v179 offset:39936
	s_cmp_eq_u32 s83, 12
	s_cbranch_scc0 .Lgu_pb_skip
	v_add_f32_e32 v221, v195, v194
	v_add_f32_e32 v253, v196, v197
	v_add_f32_e32 v221, v221, v253
	v_add_f32_e32 v222, v199, v198
	v_add_f32_e32 v253, v200, v201
	v_add_f32_e32 v222, v222, v253
	v_add_f32_e32 v223, v203, v202
	v_add_f32_e32 v253, v204, v205
	v_add_f32_e32 v223, v223, v253
	v_add_f32_e32 v224, v207, v206
	v_add_f32_e32 v253, v208, v209
	v_add_f32_e32 v224, v224, v253
	v_add_u32_e32 v253, 0x2000, v252
	global_load_dwordx4 v[194:197], v253, s[10:11]
	global_load_dwordx4 v[198:201], v253, s[10:11] offset:1024
	global_load_dwordx4 v[202:205], v253, s[10:11] offset:2048
	global_load_dwordx4 v[206:209], v253, s[10:11] offset:3072
.Lgu_pb_skip:
	global_load_lds_dwordx4 v[246:247], off
	v_lshl_add_u64 v[246:247], s[42:43], 0, v[136:137]
	s_mov_b32 m0, s76
	s_nop 0
	global_load_lds_dwordx4 v[246:247], off
	s_waitcnt vmcnt(8)
	s_waitcnt lgkmcnt(0)
	s_barrier
	s_setprio 1
	s_waitcnt lgkmcnt(0)
	v_mfma_f32_16x16x32_bf16 v[122:125], v[130:133], v[174:177], v[122:125]
	v_mfma_f32_16x16x32_bf16 v[114:117], v[150:153], v[174:177], v[114:117]
	v_mfma_f32_16x16x32_bf16 v[106:109], v[130:133], v[184:187], v[106:109]
	v_mfma_f32_16x16x32_bf16 v[98:101], v[150:153], v[184:187], v[98:101]
	v_mfma_f32_16x16x32_bf16 v[90:93], v[130:133], v[214:217], v[90:93]
	v_mfma_f32_16x16x32_bf16 v[82:85], v[150:153], v[214:217], v[82:85]
	v_mfma_f32_16x16x32_bf16 v[74:77], v[130:133], v[232:235], v[74:77]
	v_mfma_f32_16x16x32_bf16 v[66:69], v[150:153], v[232:235], v[66:69]
	v_mfma_f32_16x16x32_bf16 v[122:125], v[146:149], v[180:183], v[122:125]
	v_mfma_f32_16x16x32_bf16 v[114:117], v[154:157], v[180:183], v[114:117]
	v_mfma_f32_16x16x32_bf16 v[106:109], v[146:149], v[188:191], v[106:109]
	v_mfma_f32_16x16x32_bf16 v[98:101], v[154:157], v[188:191], v[98:101]
	v_mfma_f32_16x16x32_bf16 v[90:93], v[146:149], v[228:231], v[90:93]
	v_mfma_f32_16x16x32_bf16 v[82:85], v[154:157], v[228:231], v[82:85]
	v_mfma_f32_16x16x32_bf16 v[74:77], v[146:149], v[236:239], v[74:77]
	v_mfma_f32_16x16x32_bf16 v[66:69], v[154:157], v[236:239], v[66:69]
	s_setprio 0
	s_setprio 1
	v_mfma_f32_16x16x32_bf16 v[126:129], v[158:161], v[174:177], v[126:129]
	v_mfma_f32_16x16x32_bf16 v[118:121], v[166:169], v[174:177], v[118:121]
	v_mfma_f32_16x16x32_bf16 v[110:113], v[158:161], v[184:187], v[110:113]
	v_mfma_f32_16x16x32_bf16 v[102:105], v[166:169], v[184:187], v[102:105]
	v_mfma_f32_16x16x32_bf16 v[94:97], v[158:161], v[214:217], v[94:97]
	v_mfma_f32_16x16x32_bf16 v[86:89], v[166:169], v[214:217], v[86:89]
	v_mfma_f32_16x16x32_bf16 v[78:81], v[158:161], v[232:235], v[78:81]
	v_mfma_f32_16x16x32_bf16 v[70:73], v[166:169], v[232:235], v[70:73]
	v_mfma_f32_16x16x32_bf16 v[126:129], v[162:165], v[180:183], v[126:129]
	v_mfma_f32_16x16x32_bf16 v[118:121], v[170:173], v[180:183], v[118:121]
	v_mfma_f32_16x16x32_bf16 v[110:113], v[162:165], v[188:191], v[110:113]
	v_mfma_f32_16x16x32_bf16 v[102:105], v[170:173], v[188:191], v[102:105]
	v_mfma_f32_16x16x32_bf16 v[94:97], v[162:165], v[228:231], v[94:97]
	v_mfma_f32_16x16x32_bf16 v[86:89], v[170:173], v[228:231], v[86:89]
	v_mfma_f32_16x16x32_bf16 v[78:81], v[162:165], v[236:239], v[78:81]
	v_mfma_f32_16x16x32_bf16 v[70:73], v[170:173], v[236:239], v[70:73]
	s_setprio 0
	s_barrier
	s_add_i32 s0, s0, s72
	v_lshl_add_u64 v[218:219], v[218:219], 0, s[52:53]
	s_mov_b32 m0, s0
	ds_read_b128 v[174:177], v179 offset:49152
	ds_read_b128 v[180:183], v179 offset:50176
	ds_read_b128 v[184:187], v179 offset:51200
	ds_read_b128 v[188:191], v179 offset:52224
	ds_read_b128 v[214:217], v179 offset:53248
	ds_read_b128 v[228:231], v179 offset:54272
	ds_read_b128 v[232:235], v179 offset:55296
	ds_read_b128 v[236:239], v179 offset:56320
	global_load_lds_dwordx4 v[218:219], off
	s_add_i32 m0, s0, 0x2000
	s_add_u32 s24, s24, 0x40080
	v_lshl_add_u64 v[218:219], v[240:241], 0, s[52:53]
	s_addc_u32 s25, s25, 0
	s_add_i32 s0, s30, s72
	global_load_lds_dwordx4 v[218:219], off
	v_lshl_add_u64 v[218:219], s[24:25], 0, v[138:139]
	s_mov_b32 m0, s0
	s_nop 0
	global_load_lds_dwordx4 v[218:219], off
	v_lshl_add_u64 v[218:219], s[24:25], 0, v[134:135]
	s_add_i32 m0, s0, 0x2000
	s_nop 0
	global_load_lds_dwordx4 v[218:219], off
	v_lshl_add_u64 v[218:219], v[242:243], 0, s[52:53]
	s_mov_b32 m0, s79
	s_nop 0
	global_load_lds_dwordx4 v[218:219], off
	v_lshl_add_u64 v[218:219], v[244:245], 0, s[52:53]
	s_mov_b32 m0, s80
	s_nop 0
	global_load_lds_dwordx4 v[218:219], off
	s_waitcnt vmcnt(8)
	s_waitcnt lgkmcnt(0)
	s_barrier
	s_setprio 1
	s_waitcnt lgkmcnt(0)
	v_mfma_f32_16x16x32_bf16 v[58:61], v[130:133], v[174:177], v[58:61]
	v_mfma_f32_16x16x32_bf16 v[50:53], v[150:153], v[174:177], v[50:53]
	v_mfma_f32_16x16x32_bf16 v[42:45], v[130:133], v[184:187], v[42:45]
	v_mfma_f32_16x16x32_bf16 v[34:37], v[150:153], v[184:187], v[34:37]
	v_mfma_f32_16x16x32_bf16 v[26:29], v[130:133], v[214:217], v[26:29]
	v_mfma_f32_16x16x32_bf16 v[18:21], v[150:153], v[214:217], v[18:21]
	v_mfma_f32_16x16x32_bf16 v[10:13], v[130:133], v[232:235], v[10:13]
	v_mfma_f32_16x16x32_bf16 v[6:9], v[150:153], v[232:235], v[6:9]
	v_mfma_f32_16x16x32_bf16 v[58:61], v[146:149], v[180:183], v[58:61]
	v_mfma_f32_16x16x32_bf16 v[50:53], v[154:157], v[180:183], v[50:53]
	v_mfma_f32_16x16x32_bf16 v[42:45], v[146:149], v[188:191], v[42:45]
	v_mfma_f32_16x16x32_bf16 v[34:37], v[154:157], v[188:191], v[34:37]
	v_mfma_f32_16x16x32_bf16 v[26:29], v[146:149], v[228:231], v[26:29]
	v_mfma_f32_16x16x32_bf16 v[18:21], v[154:157], v[228:231], v[18:21]
	v_mfma_f32_16x16x32_bf16 v[10:13], v[146:149], v[236:239], v[10:13]
	v_mfma_f32_16x16x32_bf16 v[6:9], v[154:157], v[236:239], v[6:9]
	s_setprio 0
	s_setprio 1
	v_mfma_f32_16x16x32_bf16 v[62:65], v[158:161], v[174:177], v[62:65]
	v_mfma_f32_16x16x32_bf16 v[54:57], v[166:169], v[174:177], v[54:57]
	v_mfma_f32_16x16x32_bf16 v[46:49], v[158:161], v[184:187], v[46:49]
	v_mfma_f32_16x16x32_bf16 v[38:41], v[166:169], v[184:187], v[38:41]
	v_mfma_f32_16x16x32_bf16 v[30:33], v[158:161], v[214:217], v[30:33]
	v_mfma_f32_16x16x32_bf16 v[22:25], v[166:169], v[214:217], v[22:25]
	v_mfma_f32_16x16x32_bf16 v[14:17], v[158:161], v[232:235], v[14:17]
	v_mfma_f32_16x16x32_bf16 v[2:5], v[166:169], v[232:235], v[2:5]
	v_mfma_f32_16x16x32_bf16 v[62:65], v[162:165], v[180:183], v[62:65]
	v_mfma_f32_16x16x32_bf16 v[54:57], v[170:173], v[180:183], v[54:57]
	v_mfma_f32_16x16x32_bf16 v[46:49], v[162:165], v[188:191], v[46:49]
	v_mfma_f32_16x16x32_bf16 v[38:41], v[170:173], v[188:191], v[38:41]
	v_mfma_f32_16x16x32_bf16 v[30:33], v[162:165], v[228:231], v[30:33]
	v_mfma_f32_16x16x32_bf16 v[22:25], v[170:173], v[228:231], v[22:25]
	v_mfma_f32_16x16x32_bf16 v[14:17], v[162:165], v[236:239], v[14:17]
	v_mfma_f32_16x16x32_bf16 v[2:5], v[170:173], v[236:239], v[2:5]
	s_setprio 0
	s_barrier
	s_add_i32 s83, s83, 2
	s_add_u32 s71, s71, 0x100
	s_addc_u32 s82, s82, 0
	s_add_u32 s2, s2, 0x100
	s_addc_u32 s3, s3, 0
	s_cmp_gt_u32 s83, 13
	s_cbranch_scc0 .LBB0_1103
	s_and_b64 vcc, exec, s[12:13]
	s_cbranch_vccz .LBB0_1106
	s_barrier
.LBB0_1106:
	s_lshl_b32 s0, s29, 8
	v_mov_b32_e32 v0, v193
	s_add_i32 s0, s0, s77
	v_pk_mul_f32 v[128:129], v[124:125], v[128:129]
	v_bfe_u32 v180, v0, 4, 2
	v_and_or_b32 v160, v0, 15, s0
	v_lshlrev_b32_e32 v0, 4, v180
	v_ashrrev_i32_e32 v161, 31, v160
	v_lshl_add_u64 v[130:131], s[10:11], 0, v[0:1]
	v_lshlrev_b64 v[132:133], 6, v[160:161]
	v_lshl_add_u64 v[132:133], v[130:131], 0, v[132:133]
	v_or_b32_e32 v158, 16, v160
	v_ashrrev_i32_e32 v159, 31, v158
	v_or_b32_e32 v156, 32, v160
	v_ashrrev_i32_e32 v157, 31, v156
	v_or_b32_e32 v154, 48, v160
	v_ashrrev_i32_e32 v155, 31, v154
	v_add_u32_e32 v152, 0x80, v160
	v_ashrrev_i32_e32 v153, 31, v152
	v_add_u32_e32 v150, 0x90, v160
	v_ashrrev_i32_e32 v151, 31, v150
	s_mov_b32 s0, 0x358637bd
	v_pk_mul_f32 v[120:121], v[116:117], v[120:121]
	v_pk_mul_f32 v[112:113], v[108:109], v[112:113]
	v_pk_mul_f32 v[104:105], v[100:101], v[104:105]
	v_pk_mul_f32 v[96:97], v[92:93], v[96:97]
	v_pk_mul_f32 v[88:89], v[84:85], v[88:89]
	v_pk_mul_f32 v[80:81], v[76:77], v[80:81]
	v_pk_mul_f32 v[72:73], v[68:69], v[72:73]
	v_pk_mul_f32 v[64:65], v[60:61], v[64:65]
	v_pk_mul_f32 v[56:57], v[52:53], v[56:57]
	v_pk_mul_f32 v[48:49], v[44:45], v[48:49]
	v_pk_mul_f32 v[40:41], v[36:37], v[40:41]
	v_pk_mul_f32 v[32:33], v[28:29], v[32:33]
	v_pk_mul_f32 v[24:25], v[20:21], v[24:25]
	v_pk_mul_f32 v[16:17], v[12:13], v[16:17]
	v_pk_mul_f32 v[2:3], v[6:7], v[2:3]
	v_pk_mul_f32 v[4:5], v[8:9], v[4:5]
	s_waitcnt lgkmcnt(0)
	v_mov_b32_e32 v0, v221
	ds_swizzle_b32 v132, v0 offset:swizzle(SWAP,16)
	s_waitcnt lgkmcnt(0)
	v_add_f32_e32 v163, v0, v132
	v_mov_b32_e32 v165, v163
	s_nop 1
	v_permlane32_swap_b32_e32 v163, v165
	s_waitcnt lgkmcnt(0)
	v_mov_b32_e32 v0, v222
	ds_swizzle_b32 v132, v0 offset:swizzle(SWAP,16)
	s_waitcnt lgkmcnt(0)
	v_add_f32_e32 v166, v0, v132
	v_mov_b32_e32 v168, v166
	s_nop 1
	v_permlane32_swap_b32_e32 v166, v168
	s_waitcnt lgkmcnt(0)
	v_mov_b32_e32 v0, v223
	ds_swizzle_b32 v132, v0 offset:swizzle(SWAP,16)
	s_waitcnt lgkmcnt(0)
	v_add_f32_e32 v167, v0, v132
	v_mov_b32_e32 v169, v167
	s_nop 1
	v_permlane32_swap_b32_e32 v167, v169
	v_pk_add_f32 v[166:167], v[166:167], v[168:169]
	s_waitcnt lgkmcnt(0)
	v_mov_b32_e32 v0, v224
	ds_swizzle_b32 v132, v0 offset:swizzle(SWAP,16)
	s_waitcnt lgkmcnt(0)
	v_add_f32_e32 v170, v0, v132
	v_mov_b32_e32 v172, v170
	s_nop 1
	v_permlane32_swap_b32_e32 v170, v172
	s_waitcnt lgkmcnt(0)
	v_mov_b32_e32 v132, v195
	v_mov_b32_e32 v133, v196
	v_mov_b32_e32 v195, v197
	v_pk_add_f32 v[132:133], v[132:133], v[194:195]
	s_nop 0
	v_add_f32_e32 v0, v132, v133
	ds_swizzle_b32 v132, v0 offset:swizzle(SWAP,16)
	s_waitcnt lgkmcnt(0)
	v_add_f32_e32 v171, v0, v132
	v_mov_b32_e32 v173, v171
	s_nop 1
	v_permlane32_swap_b32_e32 v171, v173
	v_pk_add_f32 v[170:171], v[170:171], v[172:173]
	s_waitcnt lgkmcnt(0)
	v_mov_b32_e32 v132, v199
	v_mov_b32_e32 v133, v200
	v_mov_b32_e32 v199, v201
	v_pk_add_f32 v[132:133], v[132:133], v[198:199]
	v_add_u32_e32 v148, 0xa0, v160
	v_add_f32_e32 v0, v132, v133
	ds_swizzle_b32 v132, v0 offset:swizzle(SWAP,16)
	v_ashrrev_i32_e32 v149, 31, v148
	v_add_u32_e32 v146, 0xb0, v160
	v_ashrrev_i32_e32 v147, 31, v146
	s_waitcnt lgkmcnt(0)
	v_add_f32_e32 v174, v0, v132
	v_mov_b32_e32 v176, v174
	s_nop 1
	v_permlane32_swap_b32_e32 v174, v176
	s_waitcnt lgkmcnt(0)
	v_mov_b32_e32 v132, v203
	v_mov_b32_e32 v133, v204
	v_mov_b32_e32 v203, v205
	v_pk_add_f32 v[132:133], v[132:133], v[202:203]
	s_nop 0
	v_add_f32_e32 v0, v132, v133
	ds_swizzle_b32 v132, v0 offset:swizzle(SWAP,16)
	s_waitcnt lgkmcnt(0)
	v_add_f32_e32 v175, v0, v132
	v_mov_b32_e32 v177, v175
	s_nop 1
	v_permlane32_swap_b32_e32 v175, v177
	v_pk_add_f32 v[174:175], v[174:175], v[176:177]
	v_mov_b64_e32 v[176:177], s[0:1]
	v_pk_fma_f32 v[174:175], v[174:175], s[62:63], v[176:177] op_sel_hi:[1,0,0]
	v_pk_fma_f32 v[170:171], v[170:171], s[62:63], v[176:177] op_sel_hi:[1,0,0]
	v_mul_f32_e32 v0, 0x4b800000, v175
	v_cmp_gt_f32_e64 s[2:3], s60, v175
	v_cmp_gt_f32_e32 vcc, s60, v174
	v_pk_fma_f32 v[166:167], v[166:167], s[62:63], v[176:177] op_sel_hi:[1,0,0]
	v_cndmask_b32_e64 v0, v175, v0, s[2:3]
	v_rsq_f32_e32 v0, v0
	s_lshl_b32 s0, s28, 7
	v_mul_f32_e32 v147, 0x45800000, v0
	v_cndmask_b32_e64 v147, v0, v147, s[2:3]
	v_mul_f32_e32 v0, 0x4b800000, v174
	v_cndmask_b32_e32 v0, v174, v0, vcc
	v_rsq_f32_e32 v0, v0
	v_cmp_gt_f32_e64 s[2:3], s60, v171
	v_mul_f32_e32 v149, 0x45800000, v0
	v_cndmask_b32_e32 v149, v0, v149, vcc
	v_mul_f32_e32 v0, 0x4b800000, v171
	v_cndmask_b32_e64 v0, v171, v0, s[2:3]
	v_rsq_f32_e32 v0, v0
	v_cmp_gt_f32_e32 vcc, s60, v170
	v_mul_f32_e32 v151, 0x45800000, v0
	v_cndmask_b32_e64 v151, v0, v151, s[2:3]
	v_mul_f32_e32 v0, 0x4b800000, v170
	v_cndmask_b32_e32 v0, v170, v0, vcc
	v_rsq_f32_e32 v0, v0
	v_cmp_gt_f32_e64 s[2:3], s60, v167
	v_mul_f32_e32 v153, 0x45800000, v0
	v_cndmask_b32_e32 v153, v0, v153, vcc
	v_mul_f32_e32 v0, 0x4b800000, v167
	v_cndmask_b32_e64 v0, v167, v0, s[2:3]
	v_rsq_f32_e32 v0, v0
	v_cmp_gt_f32_e32 vcc, s60, v166
	v_mul_f32_e32 v155, 0x45800000, v0
	v_cndmask_b32_e64 v155, v0, v155, s[2:3]
	v_mul_f32_e32 v0, 0x4b800000, v166
	v_cndmask_b32_e32 v0, v166, v0, vcc
	v_rsq_f32_e32 v0, v0
	s_waitcnt lgkmcnt(0)
	v_mov_b32_e32 v166, v207
	v_mov_b32_e32 v167, v208
	v_mov_b32_e32 v207, v209
	v_mul_f32_e32 v157, 0x45800000, v0
	v_pk_add_f32 v[130:131], v[166:167], v[206:207]
	v_cndmask_b32_e32 v157, v0, v157, vcc
	v_add_f32_e32 v0, v130, v131
	ds_swizzle_b32 v130, v0 offset:swizzle(SWAP,16)
	s_waitcnt lgkmcnt(0)
	v_add_f32_e32 v162, v0, v130
	v_mov_b32_e32 v164, v162
	s_nop 1
	v_permlane32_swap_b32_e32 v162, v164
	v_pk_add_f32 v[130:131], v[162:163], v[164:165]
	s_nop 0
	v_pk_fma_f32 v[130:131], v[130:131], s[62:63], v[176:177] op_sel_hi:[1,0,0]
	s_nop 0
	v_mul_f32_e32 v0, 0x4b800000, v131
	v_cmp_gt_f32_e64 s[2:3], s60, v131
	v_cmp_gt_f32_e32 vcc, s60, v130
	s_nop 0
	v_cndmask_b32_e64 v0, v131, v0, s[2:3]
	v_rsq_f32_e32 v0, v0
	s_nop 0
	v_mul_f32_e32 v131, 0x45800000, v0
	v_cndmask_b32_e64 v159, v0, v131, s[2:3]
	v_mul_f32_e32 v163, 0xbfb8aa3b, v159
	v_mul_f32_e32 v162, v159, v159
	v_mul_f32_e32 v159, v122, v163
	v_exp_f32_e32 v159, v159
	v_mul_f32_e32 v0, 0x4b800000, v130
	v_cndmask_b32_e32 v0, v130, v0, vcc
	v_rsq_f32_e32 v0, v0
	v_add_f32_e32 v159, 1.0, v159
	v_rcp_f32_e32 v164, v159
	v_mul_f32_e32 v159, v123, v163
	v_exp_f32_e32 v159, v159
	v_pk_mul_f32 v[122:123], v[122:123], v[126:127]
	v_mul_f32_e32 v130, 0x45800000, v0
	v_cndmask_b32_e32 v0, v0, v130, vcc
	v_add_f32_e32 v159, 1.0, v159
	v_rcp_f32_e32 v165, v159
	v_lshl_or_b32 v130, v180, 3, s0
	v_or_b32_e32 v132, s78, v130
	v_ashrrev_i32_e32 v133, 31, v132
	v_pk_mul_f32 v[126:127], v[162:163], v[164:165] op_sel_hi:[0,1]
	v_pk_mul_f32 v[122:123], v[122:123], v[126:127]
	v_mov_b64_e32 v[130:131], s[8:9]
	v_cvt_pk_bf16_f32 v122, v122, v123
	v_mul_f32_e32 v123, v124, v163
	v_exp_f32_e32 v123, v123
	v_mad_i64_i32 v[160:161], s[2:3], v160, s70, v[130:131]
	v_lshlrev_b64 v[132:133], 1, v[132:133]
	v_add_f32_e32 v123, 1.0, v123
	v_rcp_f32_e32 v124, v123
	v_mul_f32_e32 v123, v125, v163
	v_exp_f32_e32 v123, v123
	v_lshl_add_u64 v[160:161], v[160:161], 0, v[132:133]
	s_andn2_b64 vcc, exec, s[38:39]
	v_add_f32_e32 v123, 1.0, v123
	v_rcp_f32_e32 v125, v123
	s_nop 0
	v_pk_mul_f32 v[124:125], v[162:163], v[124:125] op_sel_hi:[0,1]
	v_pk_mul_f32 v[124:125], v[128:129], v[124:125]
	s_nop 0
	v_cvt_pk_bf16_f32 v123, v124, v125
	v_mul_f32_e32 v124, v114, v163
	v_mul_f32_e32 v125, v115, v163
	v_exp_f32_e32 v124, v124
	v_exp_f32_e32 v125, v125
	v_pk_mul_f32 v[114:115], v[114:115], v[118:119]
	v_add_f32_e32 v124, 1.0, v124
	v_add_f32_e32 v125, 1.0, v125
	v_rcp_f32_e32 v124, v124
	v_rcp_f32_e32 v125, v125
	s_nop 0
	v_pk_mul_f32 v[118:119], v[162:163], v[124:125] op_sel_hi:[0,1]
	v_pk_mul_f32 v[114:115], v[114:115], v[118:119]
	s_nop 0
	v_cvt_pk_bf16_f32 v124, v114, v115
	v_mul_f32_e32 v115, v117, v163
	v_mul_f32_e32 v117, 0xbfb8aa3b, v157
	v_mul_f32_e32 v118, v106, v117
	v_mul_f32_e32 v119, v107, v117
	v_exp_f32_e32 v118, v118
	v_exp_f32_e32 v119, v119
	v_mul_f32_e32 v114, v116, v163
	v_mul_f32_e32 v116, v157, v157
	v_add_f32_e32 v118, 1.0, v118
	v_add_f32_e32 v119, 1.0, v119
	v_rcp_f32_e32 v118, v118
	v_rcp_f32_e32 v119, v119
	v_pk_mul_f32 v[106:107], v[106:107], v[110:111]
	v_exp_f32_e32 v114, v114
	v_exp_f32_e32 v115, v115
	v_pk_mul_f32 v[110:111], v[116:117], v[118:119] op_sel_hi:[0,1]
	v_pk_mul_f32 v[106:107], v[106:107], v[110:111]
	v_add_f32_e32 v114, 1.0, v114
	v_cvt_pk_bf16_f32 v106, v106, v107
	v_mul_f32_e32 v107, v108, v117
	v_exp_f32_e32 v107, v107
	v_add_f32_e32 v115, 1.0, v115
	v_rcp_f32_e32 v114, v114
	v_rcp_f32_e32 v115, v115
	v_add_f32_e32 v107, 1.0, v107
	v_rcp_f32_e32 v108, v107
	v_mul_f32_e32 v107, v109, v117
	v_exp_f32_e32 v107, v107
	v_pk_mul_f32 v[114:115], v[162:163], v[114:115] op_sel_hi:[0,1]
	v_pk_mul_f32 v[114:115], v[120:121], v[114:115]
	v_add_f32_e32 v107, 1.0, v107
	v_rcp_f32_e32 v109, v107
	v_cvt_pk_bf16_f32 v125, v114, v115
	v_mad_i64_i32 v[114:115], s[2:3], v158, s70, v[130:131]
	v_pk_mul_f32 v[108:109], v[116:117], v[108:109] op_sel_hi:[0,1]
	v_pk_mul_f32 v[108:109], v[112:113], v[108:109]
	v_lshl_add_u64 v[114:115], v[114:115], 0, v[132:133]
	v_cvt_pk_bf16_f32 v107, v108, v109
	v_mul_f32_e32 v108, v98, v117
	v_mul_f32_e32 v109, v99, v117
	v_exp_f32_e32 v108, v108
	v_exp_f32_e32 v109, v109
	v_pk_mul_f32 v[98:99], v[98:99], v[102:103]
	flat_store_dwordx4 v[160:161], v[122:125]
	v_add_f32_e32 v108, 1.0, v108
	v_add_f32_e32 v109, 1.0, v109
	v_rcp_f32_e32 v108, v108
	v_rcp_f32_e32 v109, v109
	s_nop 0
	v_pk_mul_f32 v[102:103], v[116:117], v[108:109] op_sel_hi:[0,1]
	v_pk_mul_f32 v[98:99], v[98:99], v[102:103]
	s_nop 0
	v_cvt_pk_bf16_f32 v108, v98, v99
	v_mul_f32_e32 v99, v101, v117
	v_mul_f32_e32 v101, 0xbfb8aa3b, v155
	v_mul_f32_e32 v102, v90, v101
	v_mul_f32_e32 v103, v91, v101
	v_exp_f32_e32 v102, v102
	v_exp_f32_e32 v103, v103
	v_mul_f32_e32 v98, v100, v117
	v_mul_f32_e32 v100, v155, v155
	v_add_f32_e32 v102, 1.0, v102
	v_add_f32_e32 v103, 1.0, v103
	v_rcp_f32_e32 v102, v102
	v_rcp_f32_e32 v103, v103
	v_pk_mul_f32 v[90:91], v[90:91], v[94:95]
	v_exp_f32_e32 v98, v98
	v_exp_f32_e32 v99, v99
	v_pk_mul_f32 v[94:95], v[100:101], v[102:103] op_sel_hi:[0,1]
	v_pk_mul_f32 v[90:91], v[90:91], v[94:95]
	v_add_f32_e32 v98, 1.0, v98
	v_cvt_pk_bf16_f32 v90, v90, v91
	v_mul_f32_e32 v91, v92, v101
	v_exp_f32_e32 v91, v91
	v_add_f32_e32 v99, 1.0, v99
	v_rcp_f32_e32 v98, v98
	v_rcp_f32_e32 v99, v99
	v_add_f32_e32 v91, 1.0, v91
	v_rcp_f32_e32 v92, v91
	v_mul_f32_e32 v91, v93, v101
	v_exp_f32_e32 v91, v91
	v_pk_mul_f32 v[98:99], v[116:117], v[98:99] op_sel_hi:[0,1]
	v_pk_mul_f32 v[98:99], v[104:105], v[98:99]
	v_add_f32_e32 v91, 1.0, v91
	v_rcp_f32_e32 v93, v91
	v_cvt_pk_bf16_f32 v109, v98, v99
	v_mad_i64_i32 v[98:99], s[2:3], v156, s70, v[130:131]
	v_pk_mul_f32 v[92:93], v[100:101], v[92:93] op_sel_hi:[0,1]
	v_pk_mul_f32 v[92:93], v[96:97], v[92:93]
	v_lshl_add_u64 v[98:99], v[98:99], 0, v[132:133]
	v_cvt_pk_bf16_f32 v91, v92, v93
	v_mul_f32_e32 v92, v82, v101
	v_mul_f32_e32 v93, v83, v101
	v_exp_f32_e32 v92, v92
	v_exp_f32_e32 v93, v93
	v_pk_mul_f32 v[82:83], v[82:83], v[86:87]
	flat_store_dwordx4 v[114:115], v[106:109]
	v_add_f32_e32 v92, 1.0, v92
	v_add_f32_e32 v93, 1.0, v93
	v_rcp_f32_e32 v92, v92
	v_rcp_f32_e32 v93, v93
	s_nop 0
	v_pk_mul_f32 v[86:87], v[100:101], v[92:93] op_sel_hi:[0,1]
	v_pk_mul_f32 v[82:83], v[82:83], v[86:87]
	s_nop 0
	v_cvt_pk_bf16_f32 v92, v82, v83
	v_mul_f32_e32 v83, v85, v101
	v_mul_f32_e32 v85, 0xbfb8aa3b, v153
	v_mul_f32_e32 v86, v74, v85
	v_mul_f32_e32 v87, v75, v85
	v_exp_f32_e32 v86, v86
	v_exp_f32_e32 v87, v87
	v_mul_f32_e32 v82, v84, v101
	v_mul_f32_e32 v84, v153, v153
	v_add_f32_e32 v86, 1.0, v86
	v_add_f32_e32 v87, 1.0, v87
	v_rcp_f32_e32 v86, v86
	v_rcp_f32_e32 v87, v87
	v_pk_mul_f32 v[74:75], v[74:75], v[78:79]
	v_exp_f32_e32 v82, v82
	v_exp_f32_e32 v83, v83
	v_pk_mul_f32 v[78:79], v[84:85], v[86:87] op_sel_hi:[0,1]
	v_pk_mul_f32 v[74:75], v[74:75], v[78:79]
	v_add_f32_e32 v82, 1.0, v82
	v_cvt_pk_bf16_f32 v74, v74, v75
	v_mul_f32_e32 v75, v76, v85
	v_exp_f32_e32 v75, v75
	v_add_f32_e32 v83, 1.0, v83
	v_rcp_f32_e32 v82, v82
	v_rcp_f32_e32 v83, v83
	v_add_f32_e32 v75, 1.0, v75
	v_rcp_f32_e32 v76, v75
	v_mul_f32_e32 v75, v77, v85
	v_exp_f32_e32 v75, v75
	v_pk_mul_f32 v[82:83], v[100:101], v[82:83] op_sel_hi:[0,1]
	v_pk_mul_f32 v[82:83], v[88:89], v[82:83]
	v_add_f32_e32 v75, 1.0, v75
	v_rcp_f32_e32 v77, v75
	v_cvt_pk_bf16_f32 v93, v82, v83
	v_mad_i64_i32 v[82:83], s[2:3], v154, s70, v[130:131]
	v_pk_mul_f32 v[76:77], v[84:85], v[76:77] op_sel_hi:[0,1]
	v_pk_mul_f32 v[76:77], v[80:81], v[76:77]
	v_lshl_add_u64 v[82:83], v[82:83], 0, v[132:133]
	v_cvt_pk_bf16_f32 v75, v76, v77
	v_mul_f32_e32 v76, v66, v85
	v_mul_f32_e32 v77, v67, v85
	v_exp_f32_e32 v76, v76
	v_exp_f32_e32 v77, v77
	v_pk_mul_f32 v[66:67], v[66:67], v[70:71]
	flat_store_dwordx4 v[98:99], v[90:93]
	v_add_f32_e32 v76, 1.0, v76
	v_add_f32_e32 v77, 1.0, v77
	v_rcp_f32_e32 v76, v76
	v_rcp_f32_e32 v77, v77
	s_nop 0
	v_pk_mul_f32 v[70:71], v[84:85], v[76:77] op_sel_hi:[0,1]
	v_pk_mul_f32 v[66:67], v[66:67], v[70:71]
	s_nop 0
	v_cvt_pk_bf16_f32 v76, v66, v67
	v_mul_f32_e32 v67, v69, v85
	v_mul_f32_e32 v69, 0xbfb8aa3b, v151
	v_mul_f32_e32 v70, v58, v69
	v_mul_f32_e32 v71, v59, v69
	v_exp_f32_e32 v70, v70
	v_exp_f32_e32 v71, v71
	v_mul_f32_e32 v66, v68, v85
	v_mul_f32_e32 v68, v151, v151
	v_add_f32_e32 v70, 1.0, v70
	v_add_f32_e32 v71, 1.0, v71
	v_rcp_f32_e32 v70, v70
	v_rcp_f32_e32 v71, v71
	v_pk_mul_f32 v[58:59], v[58:59], v[62:63]
	v_exp_f32_e32 v66, v66
	v_exp_f32_e32 v67, v67
	v_pk_mul_f32 v[62:63], v[68:69], v[70:71] op_sel_hi:[0,1]
	v_pk_mul_f32 v[58:59], v[58:59], v[62:63]
	v_add_f32_e32 v66, 1.0, v66
	v_cvt_pk_bf16_f32 v58, v58, v59
	v_mul_f32_e32 v59, v60, v69
	v_exp_f32_e32 v59, v59
	v_add_f32_e32 v67, 1.0, v67
	v_rcp_f32_e32 v66, v66
	v_rcp_f32_e32 v67, v67
	v_add_f32_e32 v59, 1.0, v59
	v_rcp_f32_e32 v60, v59
	v_mul_f32_e32 v59, v61, v69
	v_exp_f32_e32 v59, v59
	v_pk_mul_f32 v[66:67], v[84:85], v[66:67] op_sel_hi:[0,1]
	v_pk_mul_f32 v[66:67], v[72:73], v[66:67]
	v_add_f32_e32 v59, 1.0, v59
	v_rcp_f32_e32 v61, v59
	v_cvt_pk_bf16_f32 v77, v66, v67
	v_mad_i64_i32 v[66:67], s[2:3], v152, s70, v[130:131]
	v_pk_mul_f32 v[60:61], v[68:69], v[60:61] op_sel_hi:[0,1]
	v_pk_mul_f32 v[60:61], v[64:65], v[60:61]
	v_lshl_add_u64 v[66:67], v[66:67], 0, v[132:133]
	v_cvt_pk_bf16_f32 v59, v60, v61
	v_mul_f32_e32 v60, v50, v69
	v_mul_f32_e32 v61, v51, v69
	v_exp_f32_e32 v60, v60
	v_exp_f32_e32 v61, v61
	v_pk_mul_f32 v[50:51], v[50:51], v[54:55]
	flat_store_dwordx4 v[82:83], v[74:77]
	v_add_f32_e32 v60, 1.0, v60
	v_add_f32_e32 v61, 1.0, v61
	v_rcp_f32_e32 v60, v60
	v_rcp_f32_e32 v61, v61
	s_nop 0
	v_pk_mul_f32 v[54:55], v[68:69], v[60:61] op_sel_hi:[0,1]
	v_pk_mul_f32 v[50:51], v[50:51], v[54:55]
	s_nop 0
	v_cvt_pk_bf16_f32 v60, v50, v51
	v_mul_f32_e32 v51, v53, v69
	v_mul_f32_e32 v53, 0xbfb8aa3b, v149
	v_mul_f32_e32 v54, v42, v53
	v_mul_f32_e32 v55, v43, v53
	v_exp_f32_e32 v54, v54
	v_exp_f32_e32 v55, v55
	v_mul_f32_e32 v50, v52, v69
	v_mul_f32_e32 v52, v149, v149
	v_add_f32_e32 v54, 1.0, v54
	v_add_f32_e32 v55, 1.0, v55
	v_rcp_f32_e32 v54, v54
	v_rcp_f32_e32 v55, v55
	v_pk_mul_f32 v[42:43], v[42:43], v[46:47]
	v_exp_f32_e32 v50, v50
	v_exp_f32_e32 v51, v51
	v_pk_mul_f32 v[46:47], v[52:53], v[54:55] op_sel_hi:[0,1]
	v_pk_mul_f32 v[42:43], v[42:43], v[46:47]
	v_add_f32_e32 v50, 1.0, v50
	v_cvt_pk_bf16_f32 v42, v42, v43
	v_mul_f32_e32 v43, v44, v53
	v_exp_f32_e32 v43, v43
	v_add_f32_e32 v51, 1.0, v51
	v_rcp_f32_e32 v50, v50
	v_rcp_f32_e32 v51, v51
	v_add_f32_e32 v43, 1.0, v43
	v_rcp_f32_e32 v44, v43
	v_mul_f32_e32 v43, v45, v53
	v_exp_f32_e32 v43, v43
	v_pk_mul_f32 v[50:51], v[68:69], v[50:51] op_sel_hi:[0,1]
	v_pk_mul_f32 v[50:51], v[56:57], v[50:51]
	v_add_f32_e32 v43, 1.0, v43
	v_rcp_f32_e32 v45, v43
	v_cvt_pk_bf16_f32 v61, v50, v51
	v_mad_i64_i32 v[50:51], s[2:3], v150, s70, v[130:131]
	v_pk_mul_f32 v[44:45], v[52:53], v[44:45] op_sel_hi:[0,1]
	v_pk_mul_f32 v[44:45], v[48:49], v[44:45]
	v_lshl_add_u64 v[50:51], v[50:51], 0, v[132:133]
	v_cvt_pk_bf16_f32 v43, v44, v45
	v_mul_f32_e32 v44, v34, v53
	v_mul_f32_e32 v45, v35, v53
	v_exp_f32_e32 v44, v44
	v_exp_f32_e32 v45, v45
	v_pk_mul_f32 v[34:35], v[34:35], v[38:39]
	flat_store_dwordx4 v[66:67], v[58:61]
	v_add_f32_e32 v44, 1.0, v44
	v_add_f32_e32 v45, 1.0, v45
	v_rcp_f32_e32 v44, v44
	v_rcp_f32_e32 v45, v45
	s_nop 0
	v_pk_mul_f32 v[38:39], v[52:53], v[44:45] op_sel_hi:[0,1]
	v_pk_mul_f32 v[34:35], v[34:35], v[38:39]
	s_nop 0
	v_cvt_pk_bf16_f32 v44, v34, v35
	v_mul_f32_e32 v35, v37, v53
	v_mul_f32_e32 v37, 0xbfb8aa3b, v147
	v_mul_f32_e32 v38, v26, v37
	v_mul_f32_e32 v39, v27, v37
	v_exp_f32_e32 v38, v38
	v_exp_f32_e32 v39, v39
	v_mul_f32_e32 v34, v36, v53
	v_mul_f32_e32 v36, v147, v147
	v_add_f32_e32 v38, 1.0, v38
	v_add_f32_e32 v39, 1.0, v39
	v_rcp_f32_e32 v38, v38
	v_rcp_f32_e32 v39, v39
	v_pk_mul_f32 v[26:27], v[26:27], v[30:31]
	v_exp_f32_e32 v34, v34
	v_exp_f32_e32 v35, v35
	v_pk_mul_f32 v[30:31], v[36:37], v[38:39] op_sel_hi:[0,1]
	v_pk_mul_f32 v[26:27], v[26:27], v[30:31]
	v_add_f32_e32 v34, 1.0, v34
	v_cvt_pk_bf16_f32 v26, v26, v27
	v_mul_f32_e32 v27, v28, v37
	v_exp_f32_e32 v27, v27
	v_add_f32_e32 v35, 1.0, v35
	v_rcp_f32_e32 v34, v34
	v_rcp_f32_e32 v35, v35
	v_add_f32_e32 v27, 1.0, v27
	v_rcp_f32_e32 v28, v27
	v_mul_f32_e32 v27, v29, v37
	v_exp_f32_e32 v27, v27
	v_pk_mul_f32 v[34:35], v[52:53], v[34:35] op_sel_hi:[0,1]
	v_pk_mul_f32 v[34:35], v[40:41], v[34:35]
	v_add_f32_e32 v27, 1.0, v27
	v_rcp_f32_e32 v29, v27
	v_cvt_pk_bf16_f32 v45, v34, v35
	v_mad_i64_i32 v[34:35], s[2:3], v148, s70, v[130:131]
	v_pk_mul_f32 v[28:29], v[36:37], v[28:29] op_sel_hi:[0,1]
	v_pk_mul_f32 v[28:29], v[32:33], v[28:29]
	v_lshl_add_u64 v[34:35], v[34:35], 0, v[132:133]
	v_cvt_pk_bf16_f32 v27, v28, v29
	v_mul_f32_e32 v28, v18, v37
	v_mul_f32_e32 v29, v19, v37
	v_exp_f32_e32 v28, v28
	v_exp_f32_e32 v29, v29
	v_pk_mul_f32 v[18:19], v[18:19], v[22:23]
	flat_store_dwordx4 v[50:51], v[42:45]
	v_add_f32_e32 v28, 1.0, v28
	v_add_f32_e32 v29, 1.0, v29
	v_rcp_f32_e32 v28, v28
	v_rcp_f32_e32 v29, v29
	s_nop 0
	v_pk_mul_f32 v[22:23], v[36:37], v[28:29] op_sel_hi:[0,1]
	v_pk_mul_f32 v[18:19], v[18:19], v[22:23]
	v_mul_f32_e32 v22, 0xbfb8aa3b, v0
	v_cvt_pk_bf16_f32 v28, v18, v19
	v_mul_f32_e32 v18, v20, v37
	v_mul_f32_e32 v19, v21, v37
	v_mul_f32_e32 v20, v10, v22
	v_mul_f32_e32 v21, v11, v22
	v_exp_f32_e32 v20, v20
	v_exp_f32_e32 v21, v21
	v_mul_f32_e32 v0, v0, v0
	v_pk_mul_f32 v[10:11], v[10:11], v[14:15]
	v_add_f32_e32 v20, 1.0, v20
	v_add_f32_e32 v21, 1.0, v21
	v_rcp_f32_e32 v20, v20
	v_rcp_f32_e32 v21, v21
	v_exp_f32_e32 v18, v18
	v_exp_f32_e32 v19, v19
	v_pk_mul_f32 v[14:15], v[0:1], v[20:21] op_sel_hi:[0,1]
	v_pk_mul_f32 v[10:11], v[10:11], v[14:15]
	v_add_f32_e32 v18, 1.0, v18
	v_cvt_pk_bf16_f32 v10, v10, v11
	v_mul_f32_e32 v11, v12, v22
	v_exp_f32_e32 v11, v11
	v_add_f32_e32 v19, 1.0, v19
	v_rcp_f32_e32 v18, v18
	v_rcp_f32_e32 v19, v19
	v_add_f32_e32 v11, 1.0, v11
	v_rcp_f32_e32 v12, v11
	v_mul_f32_e32 v11, v13, v22
	v_exp_f32_e32 v11, v11
	v_pk_mul_f32 v[18:19], v[36:37], v[18:19] op_sel_hi:[0,1]
	v_pk_mul_f32 v[18:19], v[24:25], v[18:19]
	v_add_f32_e32 v11, 1.0, v11
	v_rcp_f32_e32 v13, v11
	v_cvt_pk_bf16_f32 v29, v18, v19
	v_mad_i64_i32 v[18:19], s[2:3], v146, s70, v[130:131]
	v_pk_mul_f32 v[12:13], v[0:1], v[12:13] op_sel_hi:[0,1]
	v_pk_mul_f32 v[12:13], v[16:17], v[12:13]
	v_lshl_add_u64 v[18:19], v[18:19], 0, v[132:133]
	v_cvt_pk_bf16_f32 v11, v12, v13
	v_mul_f32_e32 v12, v6, v22
	v_mul_f32_e32 v13, v7, v22
	v_exp_f32_e32 v12, v12
	v_exp_f32_e32 v13, v13
	s_mov_b64 s[2:3], -1
	flat_store_dwordx4 v[34:35], v[26:29]
	v_add_f32_e32 v12, 1.0, v12
	v_add_f32_e32 v13, 1.0, v13
	v_rcp_f32_e32 v12, v12
	v_rcp_f32_e32 v13, v13
	s_nop 0
	v_pk_mul_f32 v[6:7], v[0:1], v[12:13] op_sel_hi:[0,1]
	v_pk_mul_f32 v[2:3], v[2:3], v[6:7]
	s_nop 0
	v_cvt_pk_bf16_f32 v12, v2, v3
	v_mul_f32_e32 v2, v8, v22
	v_mul_f32_e32 v3, v9, v22
	v_exp_f32_e32 v2, v2
	v_exp_f32_e32 v3, v3
	v_add_f32_e32 v2, 1.0, v2
	v_add_f32_e32 v3, 1.0, v3
	v_rcp_f32_e32 v2, v2
	v_rcp_f32_e32 v3, v3
	s_nop 0
	v_pk_mul_f32 v[2:3], v[0:1], v[2:3] op_sel_hi:[0,1]
	v_pk_mul_f32 v[2:3], v[4:5], v[2:3]
	s_nop 0
	v_cvt_pk_bf16_f32 v13, v2, v3
	flat_store_dwordx4 v[18:19], v[10:13]
	s_cbranch_vccnz .LBB0_1099
	s_andn2_b64 vcc, exec, s[6:7]
	s_cbranch_vccnz .LBB0_1098
	s_barrier
	s_branch .LBB0_1098

.LBB0_1110:
	v_mov_b64_e32 v[194:195], 0xc0
	v_mov_b64_e32 v[196:197], 0xbf
	v_mov_b64_e32 v[198:199], 0x180
	v_mov_b64_e32 v[200:201], 0x17f
	v_mov_b64_e32 v[202:203], 0x200
	v_mov_b64_e32 v[204:205], 0x1ff
	v_mov_b64_e32 v[206:207], 0x100
	v_mov_b64_e32 v[208:209], 0xff
	v_mov_b32_e32 v221, 0x3e38aa3b
	v_mov_b32_e32 v222, 0x7c
	v_mov_b32_e32 v223, 0x80
	v_mov_b32_e32 v224, 0x42800000
	s_cmp_lg_u32 s25, 3
	s_cbranch_scc0 .LBB0_1218
	v_mov_b32_e32 v82, v193
	v_readlane_b32 s2, v249, 54
	v_readlane_b32 s3, v249, 55
	v_readfirstlane_b32 s0, v82
	s_ashr_i32 s51, s0, 6
	s_and_b64 vcc, exec, s[2:3]
	s_cbranch_vccz .LBB0_1163
	v_readlane_b32 s2, v249, 56
	v_readlane_b32 s3, v249, 57
	s_andn2_b64 vcc, exec, s[2:3]
	s_cbranch_vccnz .LBB0_1165
	v_readlane_b32 s2, v248, 27
	v_readlane_b32 s3, v248, 28
	s_and_b64 s[2:3], s[2:3], exec
	s_movk_i32 s0, 0x2d0
	s_cselect_b32 s63, s0, 0x280
	v_readlane_b32 s0, v249, 58
	s_add_i32 s66, s63, 0x840
	s_add_i32 s67, s51, s0
	s_cmp_ge_i32 s67, s66
	s_cbranch_scc1 .LBB0_1165
	v_readlane_b32 s0, v248, 31
	s_add_i32 s0, s0, 1
	s_lshr_b32 s24, s0, 1
	s_mul_i32 s2, s0, 0x580000
	v_readlane_b32 s6, v250, 38
	s_mul_hi_u32 s3, s0, 0x580000
	v_readlane_b32 s7, v250, 39
	s_add_u32 s2, s6, s2
	v_readlane_b32 s8, v251, 4
	s_addc_u32 s3, s7, s3
	s_mul_i32 s25, s0, 0xb00000
	v_readlane_b32 s20, v251, 16
	s_mul_hi_u32 s4, s0, 0xb00000
	v_readlane_b32 s21, v251, 17
	s_add_u32 s6, s20, s25
	s_addc_u32 s7, s21, s4
	v_readlane_b32 s20, v250, 40
	v_readlane_b32 s21, v250, 41
	s_add_u32 s20, s20, s25
	s_addc_u32 s21, s21, s4
	s_lshl_b32 s4, s0, 10
	v_readlane_b32 s72, v251, 34
	v_readlane_b32 s22, v251, 18
	s_lshl_b64 s[28:29], s[4:5], 2
	v_readlane_b32 s78, v251, 40
	v_readlane_b32 s23, v251, 19
	v_readlane_b32 s79, v251, 41
	s_add_u32 s22, s78, s28
	v_readlane_b32 s18, v251, 14
	s_addc_u32 s23, s79, s29
	s_mul_hi_u32 s4, s0, 0x1600000
	s_mul_i32 s0, s0, 0x1600000
	v_readlane_b32 s19, v251, 15
	s_add_u32 s18, s18, s0
	s_mov_b32 s25, s5
	s_addc_u32 s19, s19, s4
	s_lshl_b64 s[42:43], s[24:25], 21
	v_readlane_b32 s30, v251, 28
	v_readlane_b32 s31, v251, 29
	s_add_u32 s30, s30, s42
	v_readlane_b32 s84, v251, 46
	s_addc_u32 s31, s31, s43
	s_lshl_b64 s[44:45], s[24:25], 22
	v_readlane_b32 s85, v251, 47
	s_add_u32 s34, s84, s44
	s_addc_u32 s35, s85, s45
	s_mul_i32 s4, s24, 0x300000
	v_readlane_b32 s38, v251, 30
	s_mul_hi_u32 s0, s24, 0x300000
	v_readlane_b32 s39, v251, 31
	s_add_u32 s64, s38, s4
	v_readlane_b32 s76, v251, 38
	s_addc_u32 s65, s39, s0
	v_readlane_b32 s77, v251, 39
	s_add_u32 s38, s76, s28
	v_readlane_b32 s80, v251, 42
	s_addc_u32 s39, s77, s29
	s_mul_i32 s4, s24, 0x600000
	v_readlane_b32 s81, v251, 43
	s_mul_hi_u32 s0, s24, 0x600000
	s_add_u32 s40, s80, s4
	s_addc_u32 s41, s81, s0
	v_readlane_b32 s0, v250, 62
	s_add_u32 s78, s0, s42
	v_readlane_b32 s0, v250, 63
	v_readlane_b32 s16, v251, 12
	s_addc_u32 s79, s0, s43
	v_readlane_b32 s17, v251, 13
	s_add_u32 s80, s16, s44
	s_addc_u32 s81, s17, s45
	s_lshl_b32 s4, s24, 8
	v_readlane_b32 s10, v251, 6
	s_lshl_b64 s[28:29], s[4:5], 2
	v_readlane_b32 s11, v251, 7
	s_add_u32 s90, s10, s28
	s_addc_u32 s91, s11, s29
	s_lshl_b64 s[28:29], s[24:25], 20
	v_readlane_b32 s0, v249, 0
	s_add_u32 s94, s0, s28
	v_readlane_b32 s0, v249, 1
	v_readlane_b32 s14, v251, 10
	s_addc_u32 s95, s0, s29
	v_readlane_b32 s15, v251, 11
	s_add_u32 s10, s14, s42
	s_mul_i32 s4, s24, 0x180
	s_addc_u32 s11, s15, s43
	s_lshl_b64 s[28:29], s[4:5], 2
	v_readlane_b32 s9, v251, 5
	s_add_u32 s8, s8, s28
	s_addc_u32 s9, s9, s29
	s_mul_i32 s4, s24, 0x120000
	v_readlane_b32 s14, v249, 4
	s_mul_hi_u32 s0, s24, 0x120000
	s_add_u32 s14, s14, s4
	v_readlane_b32 s4, v249, 5
	v_readlane_b32 s12, v251, 8
	s_addc_u32 s15, s4, s0
	s_mul_i32 s4, s24, 0x240000
	v_readlane_b32 s13, v251, 9
	s_mul_hi_u32 s0, s24, 0x240000
	s_add_u32 s42, s12, s4
	s_addc_u32 s43, s13, s0
	s_mul_i32 s4, s24, 0x180000
	v_readlane_b32 s12, v249, 8
	s_mul_hi_u32 s0, s24, 0x180000
	s_add_u32 s44, s12, s4
	v_readlane_b32 s4, v249, 9
	v_readlane_b32 s86, v251, 48
	s_addc_u32 s45, s4, s0
	s_mul_i32 s4, s24, 0x2a0000
	v_readlane_b32 s87, v251, 49
	s_mul_hi_u32 s0, s24, 0x2a0000
	s_add_u32 s12, s86, s4
	s_addc_u32 s13, s87, s0
	s_lshl_b32 s0, s67, 1
	v_readlane_b32 s83, v251, 45
	s_add_i32 s4, s0, 0xfffffd60
	s_lshl_b32 s0, s63, 2
	v_readlane_b32 s73, v251, 35
	v_readlane_b32 s74, v251, 36
	v_lshlrev_b32_e32 v0, 2, v82
	v_and_b32_e32 v84, 48, v82
	s_sub_i32 s83, 0, s0
	v_readlane_b32 s0, v249, 59
	v_readlane_b32 s76, v248, 29
	v_and_b32_e32 v83, 60, v0
	v_or_b32_e32 v85, 0xffffea00, v84
	v_or_b32_e32 v86, 0xfffffa00, v84
	v_or_b32_e32 v87, 0xfffff8c0, v84
	s_lshl_b32 s84, s67, 6
	s_lshl_b32 s85, s0, 6
	s_lshl_b32 s86, s67, 2
	s_lshl_b32 s87, s0, 2
	s_lshl_b32 s88, s0, 1
	s_sub_i32 s89, 0, s63
	s_movk_i32 s71, 0x2000
	s_movk_i32 s72, 0xff
	s_movk_i32 s73, 0x1000
	s_movk_i32 s74, 0x1800
	v_readlane_b32 s77, v248, 30
	v_readlane_b32 s75, v251, 37
	v_readlane_b32 s82, v251, 44
	s_branch .LBB0_1117

	.amdhsa_kernel _Z6mk_fwd6Params
		.amdhsa_group_segment_fixed_size 0
		.amdhsa_private_segment_fixed_size 0
		.amdhsa_kernarg_size 400
		.amdhsa_user_sgpr_count 2
		.amdhsa_user_sgpr_dispatch_ptr 0
		.amdhsa_user_sgpr_queue_ptr 0
		.amdhsa_user_sgpr_kernarg_segment_ptr 1
		.amdhsa_user_sgpr_dispatch_id 0
		.amdhsa_user_sgpr_kernarg_preload_length 0
		.amdhsa_user_sgpr_kernarg_preload_offset 0
		.amdhsa_user_sgpr_private_segment_size 0
		.amdhsa_uses_dynamic_stack 0
		.amdhsa_enable_private_segment 0
		.amdhsa_system_sgpr_workgroup_id_x 1
		.amdhsa_system_sgpr_workgroup_id_y 0
		.amdhsa_system_sgpr_workgroup_id_z 0
		.amdhsa_system_sgpr_workgroup_info 0
		.amdhsa_system_vgpr_workitem_id 2
		.amdhsa_next_free_vgpr 256
		.amdhsa_next_free_sgpr 102
		.amdhsa_accum_offset 256
		.amdhsa_reserve_vcc 1
		.amdhsa_float_round_mode_32 0
		.amdhsa_float_round_mode_16_64 0
		.amdhsa_float_denorm_mode_32 3
		.amdhsa_float_denorm_mode_16_64 3
		.amdhsa_dx10_clamp 1
		.amdhsa_ieee_mode 1
		.amdhsa_fp16_overflow 0
		.amdhsa_tg_split 0
		.amdhsa_exception_fp_ieee_invalid_op 0
		.amdhsa_exception_fp_denorm_src 0
		.amdhsa_exception_fp_ieee_div_zero 0
		.amdhsa_exception_fp_ieee_overflow 0
		.amdhsa_exception_fp_ieee_underflow 0
		.amdhsa_exception_fp_ieee_inexact 0
		.amdhsa_exception_int_div_zero 0
	.end_amdhsa_kernel

amdhsa.kernels:
  - .agpr_count:     0
    .args:
      - .offset:         0
        .size:           144
        .value_kind:     by_value
      - .offset:         144
        .size:           4
        .value_kind:     hidden_block_count_x
      - .offset:         148
        .size:           4
        .value_kind:     hidden_block_count_y
      - .offset:         152
        .size:           4
        .value_kind:     hidden_block_count_z
      - .offset:         156
        .size:           2
        .value_kind:     hidden_group_size_x
      - .offset:         158
        .size:           2
        .value_kind:     hidden_group_size_y
      - .offset:         160
        .size:           2
        .value_kind:     hidden_group_size_z
      - .offset:         162
        .size:           2
        .value_kind:     hidden_remainder_x
      - .offset:         164
        .size:           2
        .value_kind:     hidden_remainder_y
      - .offset:         166
        .size:           2
        .value_kind:     hidden_remainder_z
      - .offset:         184
        .size:           8
        .value_kind:     hidden_global_offset_x
      - .offset:         192
        .size:           8
        .value_kind:     hidden_global_offset_y
      - .offset:         200
        .size:           8
        .value_kind:     hidden_global_offset_z
      - .offset:         208
        .size:           2
        .value_kind:     hidden_grid_dims
      - .offset:         232
        .size:           8
        .value_kind:     hidden_multigrid_sync_arg
      - .offset:         264
        .size:           4
        .value_kind:     hidden_dynamic_lds_size
    .group_segment_fixed_size: 0
    .kernarg_segment_align: 8
    .kernarg_segment_size: 400
    .language:       OpenCL C
    .language_version:
      - 2
      - 0
    .max_flat_workgroup_size: 512
    .name:           _Z6mk_fwd6Params
    .private_segment_fixed_size: 0
    .sgpr_count:     108
    .sgpr_spill_count: 237
    .symbol:         _Z6mk_fwd6Params.kd
    .uniform_work_group_size: 1
    .uses_dynamic_stack: false
    .vgpr_count:     256
    .vgpr_spill_count: 0
    .wavefront_size: 64
